# own lean helper (race fix: vmcnt(0) before first loop iteration) + 2x4 recurrence at 48 mod 64
# baseline (speedup 1.0000x reference)
.LBB0_533:
	s_and_b64 vcc, exec, s[0:1]
	s_cbranch_vccz .LBB0_508
	v_mov_b32_e32 v57, v241
	s_ashr_i32 s48, s8, 5
	s_bfe_u32 s9, s8, 0x40001
	v_readfirstlane_b32 s0, v57
	s_and_b32 s10, s8, 1
	s_ashr_i32 s11, s0, 6
	s_ashr_i32 s49, s48, 31
	s_cmp_gt_i32 s11, 3
	s_mov_b64 s[0:1], -1
	s_cbranch_scc0 .LBB0_606
	s_waitcnt vmcnt(0)
	v_add_u32_e32 v198, 0xffffff00, v241
	v_lshrrev_b32_e32 v206, 3, v198
	v_and_b32_e32 v207, 7, v198
	s_lshl_b32 s0, s9, 6
	v_lshl_add_u32 v208, v207, 2, s0
	v_cmp_eq_u32_e64 s[38:39], 0, v207
	v_cmp_gt_u32_e64 s[28:29], 16, v206
	s_cmp_eq_u32 s10, 0
	s_cselect_b64 s[40:41], -1, 0
	s_nop 3
	s_and_b64 s[40:41], s[40:41], s[38:39]
	v_lshlrev_b32_e32 v199, 2, v208
	v_readlane_b32 s4, v255, 32
	v_readlane_b32 s5, v255, 33
	v_readlane_b32 s12, v255, 47
	v_readlane_b32 s13, v255, 48
	v_readlane_b32 s0, v255, 49
	v_readlane_b32 s1, v255, 50
	s_nop 4
	s_add_u32 s6, s4, 0x1000
	s_addc_u32 s7, s5, 0
	global_load_dwordx4 v[0:3], v199, s[4:5]
	global_load_dwordx4 v[4:7], v199, s[4:5] offset:128
	global_load_dwordx4 v[8:11], v199, s[6:7]
	global_load_dwordx4 v[12:15], v199, s[6:7] offset:128
	s_add_u32 s6, s4, 0x2000
	s_addc_u32 s7, s5, 0
	global_load_dwordx4 v[24:27], v199, s[12:13]
	global_load_dwordx4 v[28:31], v199, s[12:13] offset:128
	global_load_dwordx4 v[16:19], v199, s[6:7]
	global_load_dwordx4 v[20:23], v199, s[6:7] offset:128
	global_load_dwordx4 v[32:35], v199, s[0:1]
	global_load_dwordx4 v[36:39], v199, s[0:1] offset:128
	global_load_dwordx4 v[40:43], v199, s[64:65]
	global_load_dwordx4 v[44:47], v199, s[64:65] offset:128
	v_mov_b32_e32 v48, 0x3fb8aa3b
	v_mov_b32_e32 v49, 0x3fb8aa3b
	s_mul_i32 s0, s48, 0x810
	v_add_u32_e32 v209, s0, v206
	v_mov_b32_e32 v211, 0
	v_lshlrev_b32_e32 v210, 1, v208
	s_movk_i32 s14, 0x1a00
	v_mad_u64_u32 v[182:183], s[0:1], v209, s14, v[210:211]
	s_add_u32 s4, s86, 0x81a7000
	s_addc_u32 s5, s87, 0
	v_lshl_add_u64 v[182:183], v[182:183], 0, s[4:5]
	s_mov_b64 s[0:1], 0x1000
	v_lshl_add_u64 v[178:179], v[182:183], 0, s[0:1]
	v_lshl_add_u64 v[180:181], v[178:179], 0, s[0:1]
	v_lshl_add_u32 v198, v209, 11, v210
	v_mov_b32_e32 v210, v198
	s_add_u32 s4, s86, 0xeb48000
	s_addc_u32 s5, s87, 0
	v_lshl_add_u64 v[186:187], v[210:211], 0, s[4:5]
	s_add_u32 s4, s86, 0x10bc8000
	s_addc_u32 s5, s87, 0
	v_lshl_add_u64 v[188:189], v[210:211], 0, s[4:5]
	s_lshl_b32 s0, s9, 6
	s_lshl_b32 s1, s10, 5
	s_add_i32 s0, s0, s1
	v_lshl_add_u32 v198, v207, 2, s0
	v_lshlrev_b32_e32 v198, 1, v198
	v_lshl_add_u32 v210, v209, 11, v198
	s_add_u32 s4, s86, 0x5700000
	s_addc_u32 s5, s87, 0
	v_lshl_add_u64 v[190:191], v[210:211], 0, s[4:5]
	s_lshl_b32 s0, s9, 2
	v_lshl_add_u32 v210, v209, 6, s0
	s_add_u32 s4, s86, 0x7884000
	s_addc_u32 s5, s87, 0
	v_lshl_add_u64 v[192:193], v[210:211], 0, s[4:5]
	v_mul_u32_u24_e32 v194, 0x600, v206
	v_lshl_add_u32 v194, v207, 4, v194
	v_lshlrev_b32_e32 v195, 7, v206
	v_lshl_add_u32 v195, v207, 4, v195
	v_add_u32_e32 v195, 0x18000, v195
	v_lshlrev_b32_e32 v196, 2, v206
	v_add_u32_e32 v196, 0x1a000, v196
	v_lshlrev_b32_e32 v197, 3, v206
	v_add_u32_e32 v197, 0x1a100, v197
	global_load_dwordx2 v[52:53], v[178:179], off
	global_load_dwordx2 v[54:55], v[178:179], off offset:64
	global_load_dwordx2 v[56:57], v[178:179], off offset:2048
	global_load_dwordx2 v[58:59], v[178:179], off offset:2112
	global_load_dwordx2 v[60:61], v[180:181], off
	global_load_dwordx2 v[62:63], v[180:181], off offset:64
	global_load_dwordx2 v[64:65], v[182:183], off offset:-2560
	global_load_dwordx2 v[66:67], v[182:183], off offset:-2496
	global_load_dwordx2 v[68:69], v[182:183], off offset:-512
	global_load_dwordx2 v[70:71], v[182:183], off offset:-448
	global_load_dwordx2 v[72:73], v[178:179], off offset:-2560
	global_load_dwordx2 v[74:75], v[178:179], off offset:-2496
	global_load_dwordx2 v[76:77], v[186:187], off
	global_load_dwordx2 v[78:79], v[186:187], off offset:64
	global_load_dwordx2 v[80:81], v[188:189], off
	global_load_dwordx2 v[82:83], v[188:189], off offset:64
	s_mov_b32 s13, 0
	s_waitcnt vmcnt(0)
	v_cmp_ne_u32_e64 s[6:7], 0, v206
	s_nop 3
	v_cndmask_b32_e64 v64, 0, v64, s[6:7]
	v_cndmask_b32_e64 v65, 0, v65, s[6:7]
	v_cndmask_b32_e64 v66, 0, v66, s[6:7]
	v_cndmask_b32_e64 v67, 0, v67, s[6:7]
	v_cndmask_b32_e64 v68, 0, v68, s[6:7]
	v_cndmask_b32_e64 v69, 0, v69, s[6:7]
	v_cndmask_b32_e64 v70, 0, v70, s[6:7]
	v_cndmask_b32_e64 v71, 0, v71, s[6:7]
	v_cndmask_b32_e64 v72, 0, v72, s[6:7]
	v_cndmask_b32_e64 v73, 0, v73, s[6:7]
	v_cndmask_b32_e64 v74, 0, v74, s[6:7]
	v_cndmask_b32_e64 v75, 0, v75, s[6:7]
	v_lshlrev_b32_e32 v84, 16, v52
	v_and_b32_e32 v85, 0xffff0000, v52
	v_lshlrev_b32_e32 v86, 16, v53
	v_and_b32_e32 v87, 0xffff0000, v53
	v_lshlrev_b32_e32 v88, 16, v54
	v_and_b32_e32 v89, 0xffff0000, v54
	v_lshlrev_b32_e32 v90, 16, v55
	v_and_b32_e32 v91, 0xffff0000, v55
	v_lshlrev_b32_e32 v124, 16, v64
	v_and_b32_e32 v125, 0xffff0000, v64
	v_lshlrev_b32_e32 v126, 16, v65
	v_and_b32_e32 v127, 0xffff0000, v65
	v_lshlrev_b32_e32 v128, 16, v66
	v_and_b32_e32 v129, 0xffff0000, v66
	v_lshlrev_b32_e32 v130, 16, v67
	v_and_b32_e32 v131, 0xffff0000, v67
	v_pk_add_f32 v[124:125], v[124:125], v[84:85] neg_lo:[0,1] neg_hi:[0,1]
	v_pk_add_f32 v[126:127], v[126:127], v[86:87] neg_lo:[0,1] neg_hi:[0,1]
	v_pk_add_f32 v[128:129], v[128:129], v[88:89] neg_lo:[0,1] neg_hi:[0,1]
	v_pk_add_f32 v[130:131], v[130:131], v[90:91] neg_lo:[0,1] neg_hi:[0,1]
	v_pk_fma_f32 v[84:85], v[0:1], v[124:125], v[84:85]
	v_pk_fma_f32 v[86:87], v[2:3], v[126:127], v[86:87]
	v_pk_fma_f32 v[88:89], v[4:5], v[128:129], v[88:89]
	v_pk_fma_f32 v[90:91], v[6:7], v[130:131], v[90:91]
	v_lshlrev_b32_e32 v92, 16, v56
	v_and_b32_e32 v93, 0xffff0000, v56
	v_lshlrev_b32_e32 v94, 16, v57
	v_and_b32_e32 v95, 0xffff0000, v57
	v_lshlrev_b32_e32 v96, 16, v58
	v_and_b32_e32 v97, 0xffff0000, v58
	v_lshlrev_b32_e32 v98, 16, v59
	v_and_b32_e32 v99, 0xffff0000, v59
	v_lshlrev_b32_e32 v124, 16, v68
	v_and_b32_e32 v125, 0xffff0000, v68
	v_lshlrev_b32_e32 v126, 16, v69
	v_and_b32_e32 v127, 0xffff0000, v69
	v_lshlrev_b32_e32 v128, 16, v70
	v_and_b32_e32 v129, 0xffff0000, v70
	v_lshlrev_b32_e32 v130, 16, v71
	v_and_b32_e32 v131, 0xffff0000, v71
	v_pk_add_f32 v[124:125], v[124:125], v[92:93] neg_lo:[0,1] neg_hi:[0,1]
	v_pk_add_f32 v[126:127], v[126:127], v[94:95] neg_lo:[0,1] neg_hi:[0,1]
	v_pk_add_f32 v[128:129], v[128:129], v[96:97] neg_lo:[0,1] neg_hi:[0,1]
	v_pk_add_f32 v[130:131], v[130:131], v[98:99] neg_lo:[0,1] neg_hi:[0,1]
	v_pk_fma_f32 v[92:93], v[8:9], v[124:125], v[92:93]
	v_pk_fma_f32 v[94:95], v[10:11], v[126:127], v[94:95]
	v_pk_fma_f32 v[96:97], v[12:13], v[128:129], v[96:97]
	v_pk_fma_f32 v[98:99], v[14:15], v[130:131], v[98:99]
	v_lshlrev_b32_e32 v100, 16, v60
	v_and_b32_e32 v101, 0xffff0000, v60
	v_lshlrev_b32_e32 v102, 16, v61
	v_and_b32_e32 v103, 0xffff0000, v61
	v_lshlrev_b32_e32 v104, 16, v62
	v_and_b32_e32 v105, 0xffff0000, v62
	v_lshlrev_b32_e32 v106, 16, v63
	v_and_b32_e32 v107, 0xffff0000, v63
	v_lshlrev_b32_e32 v124, 16, v72
	v_and_b32_e32 v125, 0xffff0000, v72
	v_lshlrev_b32_e32 v126, 16, v73
	v_and_b32_e32 v127, 0xffff0000, v73
	v_lshlrev_b32_e32 v128, 16, v74
	v_and_b32_e32 v129, 0xffff0000, v74
	v_lshlrev_b32_e32 v130, 16, v75
	v_and_b32_e32 v131, 0xffff0000, v75
	v_pk_add_f32 v[124:125], v[124:125], v[100:101] neg_lo:[0,1] neg_hi:[0,1]
	v_pk_add_f32 v[126:127], v[126:127], v[102:103] neg_lo:[0,1] neg_hi:[0,1]
	v_pk_add_f32 v[128:129], v[128:129], v[104:105] neg_lo:[0,1] neg_hi:[0,1]
	v_pk_add_f32 v[130:131], v[130:131], v[106:107] neg_lo:[0,1] neg_hi:[0,1]
	v_pk_fma_f32 v[100:101], v[16:17], v[124:125], v[100:101]
	v_pk_fma_f32 v[102:103], v[18:19], v[126:127], v[102:103]
	v_pk_fma_f32 v[104:105], v[20:21], v[128:129], v[104:105]
	v_pk_fma_f32 v[106:107], v[22:23], v[130:131], v[106:107]
	v_lshlrev_b32_e32 v108, 16, v80
	v_and_b32_e32 v109, 0xffff0000, v80
	v_lshlrev_b32_e32 v110, 16, v81
	v_and_b32_e32 v111, 0xffff0000, v81
	v_lshlrev_b32_e32 v112, 16, v82
	v_and_b32_e32 v113, 0xffff0000, v82
	v_lshlrev_b32_e32 v114, 16, v83
	v_and_b32_e32 v115, 0xffff0000, v83
	v_lshlrev_b32_e32 v116, 16, v76
	v_and_b32_e32 v117, 0xffff0000, v76
	v_lshlrev_b32_e32 v118, 16, v77
	v_and_b32_e32 v119, 0xffff0000, v77
	v_lshlrev_b32_e32 v120, 16, v78
	v_and_b32_e32 v121, 0xffff0000, v78
	v_lshlrev_b32_e32 v122, 16, v79
	v_and_b32_e32 v123, 0xffff0000, v79
	v_pk_mul_f32 v[132:133], v[92:93], v[24:25]
	v_pk_mul_f32 v[134:135], v[94:95], v[26:27]
	v_pk_mul_f32 v[136:137], v[96:97], v[28:29]
	v_pk_mul_f32 v[138:139], v[98:99], v[30:31]
	v_pk_add_f32 v[124:125], v[108:109], -1.0 op_sel_hi:[1,0]
	v_pk_add_f32 v[126:127], v[110:111], -1.0 op_sel_hi:[1,0]
	v_pk_add_f32 v[128:129], v[112:113], -1.0 op_sel_hi:[1,0]
	v_pk_add_f32 v[130:131], v[114:115], -1.0 op_sel_hi:[1,0]
	v_pk_fma_f32 v[124:125], v[32:33], v[124:125], 1.0 op_sel_hi:[1,1,0]
	v_pk_fma_f32 v[126:127], v[34:35], v[126:127], 1.0 op_sel_hi:[1,1,0]
	v_pk_fma_f32 v[128:129], v[36:37], v[128:129], 1.0 op_sel_hi:[1,1,0]
	v_pk_fma_f32 v[130:131], v[38:39], v[130:131], 1.0 op_sel_hi:[1,1,0]
	v_pk_mul_f32 v[140:141], v[124:125], v[92:93]
	v_pk_mul_f32 v[142:143], v[126:127], v[94:95]
	v_pk_mul_f32 v[144:145], v[128:129], v[96:97]
	v_pk_mul_f32 v[146:147], v[130:131], v[98:99]
	v_pk_mul_f32 v[148:149], v[84:85], v[140:141]
	v_pk_mul_f32 v[150:151], v[86:87], v[142:143]
	v_pk_mul_f32 v[152:153], v[88:89], v[144:145]
	v_pk_mul_f32 v[154:155], v[90:91], v[146:147]
	v_pk_mul_f32 v[156:157], v[132:133], v[108:109]
	v_pk_mul_f32 v[158:159], v[134:135], v[110:111]
	v_pk_mul_f32 v[160:161], v[136:137], v[112:113]
	v_pk_mul_f32 v[162:163], v[138:139], v[114:115]
	v_pk_mul_f32 v[124:125], v[148:149], v[40:41]
	v_pk_mul_f32 v[126:127], v[150:151], v[42:43]
	v_pk_mul_f32 v[128:129], v[152:153], v[44:45]
	v_pk_mul_f32 v[130:131], v[154:155], v[46:47]
	v_pk_add_f32 v[124:125], v[124:125], v[126:127]
	v_pk_add_f32 v[128:129], v[128:129], v[130:131]
	v_pk_add_f32 v[124:125], v[124:125], v[128:129]
	v_add_f32_e32 v173, v124, v125
	v_pk_mul_f32 v[124:125], v[156:157], v[84:85]
	v_pk_mul_f32 v[126:127], v[158:159], v[86:87]
	v_pk_mul_f32 v[128:129], v[160:161], v[88:89]
	v_pk_mul_f32 v[130:131], v[162:163], v[90:91]
	v_pk_add_f32 v[124:125], v[124:125], v[126:127]
	v_pk_add_f32 v[128:129], v[128:129], v[130:131]
	v_pk_add_f32 v[124:125], v[124:125], v[128:129]
	v_add_f32_e32 v174, v124, v125
	v_pk_mul_f32 v[124:125], v[132:133], v[132:133]
	v_pk_mul_f32 v[126:127], v[134:135], v[134:135]
	v_pk_mul_f32 v[128:129], v[136:137], v[136:137]
	v_pk_mul_f32 v[130:131], v[138:139], v[138:139]
	v_pk_add_f32 v[124:125], v[124:125], v[126:127]
	v_pk_add_f32 v[128:129], v[128:129], v[130:131]
	v_pk_add_f32 v[124:125], v[124:125], v[128:129]
	v_add_f32_e32 v172, v124, v125
	v_pk_add_f32 v[148:149], v[148:149], v[150:151]
	v_pk_add_f32 v[152:153], v[152:153], v[154:155]
	v_pk_add_f32 v[148:149], v[148:149], v[152:153]
	v_add_f32_e32 v175, v148, v149
	v_pk_mul_f32 v[116:117], v[116:117], v[48:49]
	v_pk_mul_f32 v[118:119], v[118:119], v[48:49]
	v_pk_mul_f32 v[120:121], v[120:121], v[48:49]
	v_pk_mul_f32 v[122:123], v[122:123], v[48:49]
	v_add_f32_dpp v172, v172, v172 quad_perm:[1,0,3,2] row_mask:0xf bank_mask:0xf bound_ctrl:1
	v_add_f32_dpp v173, v173, v173 quad_perm:[1,0,3,2] row_mask:0xf bank_mask:0xf bound_ctrl:1
	v_add_f32_dpp v174, v174, v174 quad_perm:[1,0,3,2] row_mask:0xf bank_mask:0xf bound_ctrl:1
	v_add_f32_dpp v175, v175, v175 quad_perm:[1,0,3,2] row_mask:0xf bank_mask:0xf bound_ctrl:1
	v_add_f32_dpp v172, v172, v172 quad_perm:[2,3,0,1] row_mask:0xf bank_mask:0xf bound_ctrl:1
	v_add_f32_dpp v173, v173, v173 quad_perm:[2,3,0,1] row_mask:0xf bank_mask:0xf bound_ctrl:1
	v_add_f32_dpp v174, v174, v174 quad_perm:[2,3,0,1] row_mask:0xf bank_mask:0xf bound_ctrl:1
	v_add_f32_dpp v175, v175, v175 quad_perm:[2,3,0,1] row_mask:0xf bank_mask:0xf bound_ctrl:1
	v_add_f32_dpp v172, v172, v172 row_half_mirror row_mask:0xf bank_mask:0xf bound_ctrl:1
	v_add_f32_dpp v173, v173, v173 row_half_mirror row_mask:0xf bank_mask:0xf bound_ctrl:1
	v_add_f32_dpp v174, v174, v174 row_half_mirror row_mask:0xf bank_mask:0xf bound_ctrl:1
	v_add_f32_dpp v175, v175, v175 row_half_mirror row_mask:0xf bank_mask:0xf bound_ctrl:1
	v_exp_f32_e32 v116, v116
	v_exp_f32_e32 v117, v117
	v_exp_f32_e32 v118, v118
	v_exp_f32_e32 v119, v119
	v_exp_f32_e32 v120, v120
	v_exp_f32_e32 v121, v121
	v_exp_f32_e32 v122, v122
	v_exp_f32_e32 v123, v123
	v_rsq_f32_e32 v176, v172
	v_pk_mul_f32 v[148:149], v[116:117], v[84:85]
	v_pk_mul_f32 v[150:151], v[118:119], v[86:87]
	v_pk_mul_f32 v[152:153], v[120:121], v[88:89]
	v_pk_mul_f32 v[154:155], v[122:123], v[90:91]
	v_min_f32_e32 v176, 0x5368d4a5, v176
	v_mul_f32_e32 v174, v174, v176
	v_pk_mul_f32 v[164:165], v[132:133], v[176:177] op_sel_hi:[1,0] neg_lo:[1,0] neg_hi:[1,0]
	v_pk_mul_f32 v[166:167], v[134:135], v[176:177] op_sel_hi:[1,0] neg_lo:[1,0] neg_hi:[1,0]
	v_pk_mul_f32 v[168:169], v[136:137], v[176:177] op_sel_hi:[1,0] neg_lo:[1,0] neg_hi:[1,0]
	v_pk_mul_f32 v[170:171], v[138:139], v[176:177] op_sel_hi:[1,0] neg_lo:[1,0] neg_hi:[1,0]
	v_pk_mul_f32 v[156:157], v[156:157], v[176:177] op_sel_hi:[1,0]
	v_pk_mul_f32 v[158:159], v[158:159], v[176:177] op_sel_hi:[1,0]
	v_pk_mul_f32 v[160:161], v[160:161], v[176:177] op_sel_hi:[1,0]
	v_pk_mul_f32 v[162:163], v[162:163], v[176:177] op_sel_hi:[1,0]
	s_mul_i32 s14, s13, 0xc000
	v_add_u32_e32 v198, s14, v194
	ds_write_b128 v198, v[148:151] offset:0
	ds_write_b128 v198, v[152:155] offset:128
	ds_write_b128 v198, v[116:119] offset:256
	ds_write_b128 v198, v[120:123] offset:384
	ds_write_b128 v198, v[140:143] offset:512
	ds_write_b128 v198, v[144:147] offset:640
	ds_write_b128 v198, v[164:167] offset:768
	ds_write_b128 v198, v[168:171] offset:896
	ds_write_b128 v198, v[156:159] offset:1024
	ds_write_b128 v198, v[160:163] offset:1152
	ds_write_b128 v198, v[100:103] offset:1280
	ds_write_b128 v198, v[104:107] offset:1408
	s_lshl_b32 s14, s13, 7
	v_add_u32_e32 v199, s14, v196
	s_lshl_b32 s14, s13, 8
	v_add_u32_e32 v198, s14, v197
	ds_write_b32 v199, v173
	ds_write_b64 v198, v[174:175]
	s_mov_b64 s[0:1], 0x34000
	v_lshl_add_u64 v[178:179], v[178:179], 0, s[0:1]
	v_lshl_add_u64 v[180:181], v[180:181], 0, s[0:1]
	v_lshl_add_u64 v[182:183], v[182:183], 0, s[0:1]
	s_mov_b64 s[0:1], 0x10000
	v_lshl_add_u64 v[186:187], v[186:187], 0, s[0:1]
	v_lshl_add_u64 v[188:189], v[188:189], 0, s[0:1]
	global_load_dwordx2 v[52:53], v[178:179], off
	global_load_dwordx2 v[54:55], v[178:179], off offset:64
	global_load_dwordx2 v[56:57], v[178:179], off offset:2048
	global_load_dwordx2 v[58:59], v[178:179], off offset:2112
	global_load_dwordx2 v[60:61], v[180:181], off
	global_load_dwordx2 v[62:63], v[180:181], off offset:64
	global_load_dwordx2 v[64:65], v[182:183], off offset:-2560
	global_load_dwordx2 v[66:67], v[182:183], off offset:-2496
	global_load_dwordx2 v[68:69], v[182:183], off offset:-512
	global_load_dwordx2 v[70:71], v[182:183], off offset:-448
	global_load_dwordx2 v[72:73], v[178:179], off offset:-2560
	global_load_dwordx2 v[74:75], v[178:179], off offset:-2496
	global_load_dwordx2 v[76:77], v[186:187], off
	global_load_dwordx2 v[78:79], v[186:187], off offset:64
	global_load_dwordx2 v[80:81], v[188:189], off
	global_load_dwordx2 v[82:83], v[188:189], off offset:64
	s_waitcnt lgkmcnt(0)
	s_barrier
	s_waitcnt vmcnt(0)
	s_mov_b32 s12, 0
